# c9 plus final-output f32 stores merged across lane halves with DPP row_ror:8 so each store writes 8 rows x 128 B full lines (13 of 16 store pairs)
# baseline (speedup 1.0000x reference)
; __device__ __forceinline__ void rstd8(float (&r)[8], const float* ssp, int row0) {
; #pragma unroll
;     for (int h = 0; h < 2; ++h) {
;         f32x4 a[4], b[4];
; #pragma unroll
;         for (int q = 0; q < 4; ++q) { const size_t o = (size_t)(row0 + h * 128 + q * 16) * 8; a[q] = *(const f32x4*)(ssp + o); b[q] = *(const f32x4*)(ssp + o + 4); }
; #pragma unroll
;         for (int q = 0; q < 4; ++q) r[h * 4 + q] = rsqrtf((((a[q].x + a[q].y) + (a[q].z + a[q].w)) + ((b[q].x + b[q].y) + (b[q].z + b[q].w))) * (1.f / D) + EPS);
;     }
; }
;     __device__ __forceinline__ void operator()(AccT& acc, const Unit& u, int wr, int wc, int fr, int fq) const {
;     ...
;         f32x4 gv[2][2];
; #pragma unroll
;         for (int bj = 0; bj < 2; ++bj) { gv[bj][0] = *(const f32x4*)(gain + col0 + bj * 128); gv[bj][1] = *(const f32x4*)(gain + col0 + bj * 128 + 4); }
;         float rs[8]; rstd8(rs, ssp, row0);
.LBB0_981:
	v_lshlrev_b64 v[196:197], 2, v[196:197]
	v_lshlrev_b64 v[18:19], 5, v[172:173]
	v_lshl_add_u64 v[6:7], s[48:49], 0, v[196:197]
	v_lshl_add_u64 v[22:23], s[6:7], 0, v[18:19]
	s_waitcnt lgkmcnt(0)
	global_load_dwordx4 v[10:13], v[6:7], off offset:16
	global_load_dwordx4 v[14:17], v[6:7], off
	global_load_dwordx4 v[2:5], v[6:7], off offset:528
	s_nop 0
	global_load_dwordx4 v[6:9], v[6:7], off offset:512
	s_nop 0
	global_load_dwordx4 v[18:21], v[22:23], off
	s_nop 0
	global_load_dwordx4 v[22:25], v[22:23], off offset:16
	v_lshlrev_b64 v[26:27], 5, v[174:175]
	v_lshl_add_u64 v[30:31], s[6:7], 0, v[26:27]
	global_load_dwordx4 v[26:29], v[30:31], off
	s_nop 0
	global_load_dwordx4 v[30:33], v[30:31], off offset:16
	v_lshlrev_b64 v[34:35], 5, v[170:171]
	v_lshl_add_u64 v[38:39], s[6:7], 0, v[34:35]
	global_load_dwordx4 v[34:37], v[38:39], off
	s_nop 0
	global_load_dwordx4 v[38:41], v[38:39], off offset:16
	v_lshlrev_b64 v[42:43], 5, v[168:169]
	v_lshl_add_u64 v[46:47], s[6:7], 0, v[42:43]
	global_load_dwordx4 v[42:45], v[46:47], off
	s_nop 0
	global_load_dwordx4 v[46:49], v[46:47], off offset:16
	s_mov_b32 s18, 0x358637bd
	s_waitcnt vmcnt(7)
	v_mov_b32_e32 v214, v18
	s_waitcnt vmcnt(6)
	v_mov_b32_e32 v215, v22
	v_mov_b32_e32 v22, v19
	v_pk_add_f32 v[18:19], v[214:215], v[22:23]
	v_mov_b32_e32 v22, v20
	v_mov_b32_e32 v23, v24
	v_mov_b32_e32 v24, v21
	v_pk_add_f32 v[20:21], v[22:23], v[24:25]
	s_waitcnt vmcnt(5)
	v_mov_b32_e32 v22, v28
	v_pk_add_f32 v[18:19], v[18:19], v[20:21]
	v_mov_b32_e32 v20, v26
	s_waitcnt vmcnt(4)
	v_mov_b32_e32 v21, v30
	v_mov_b32_e32 v30, v27
	v_mov_b32_e32 v23, v32
	v_mov_b32_e32 v32, v29
	v_pk_add_f32 v[20:21], v[20:21], v[30:31]
	v_pk_add_f32 v[22:23], v[22:23], v[32:33]
	v_mov_b64_e32 v[214:215], s[18:19]
	v_pk_add_f32 v[20:21], v[20:21], v[22:23]
	v_mov_b32_e32 v23, v18
	v_mov_b32_e32 v22, v20
	v_mov_b32_e32 v18, v21
	v_pk_add_f32 v[18:19], v[22:23], v[18:19]
	s_waitcnt vmcnt(2)
	v_mov_b32_e32 v21, v40
	v_pk_fma_f32 v[18:19], v[18:19], s[74:75], v[214:215] op_sel_hi:[1,0,0]
	v_mov_b32_e32 v40, v37
	v_mul_f32_e32 v20, 0x4b800000, v19
	v_cmp_gt_f32_e64 s[46:47], s1, v19
	v_cmp_gt_f32_e32 vcc, s1, v18
	s_waitcnt vmcnt(1)
	v_mov_b32_e32 v22, v44
	v_cndmask_b32_e64 v19, v19, v20, s[46:47]
	v_rsq_f32_e32 v19, v19
	s_waitcnt vmcnt(0)
	v_mov_b32_e32 v23, v48
	v_mov_b32_e32 v48, v45
	v_pk_add_f32 v[22:23], v[22:23], v[48:49]
	v_mul_f32_e32 v20, 0x45800000, v19
	v_cndmask_b32_e64 v212, v19, v20, s[46:47]
	v_mul_f32_e32 v19, 0x4b800000, v18
	v_cndmask_b32_e32 v18, v18, v19, vcc
	v_rsq_f32_e32 v18, v18
	v_mov_b32_e32 v20, v36
	v_pk_add_f32 v[20:21], v[20:21], v[40:41]
	s_mov_b64 s[18:19], -1
	v_mul_f32_e32 v19, 0x45800000, v18
	v_cndmask_b32_e32 v210, v18, v19, vcc
	v_mov_b32_e32 v18, v34
	v_mov_b32_e32 v19, v38
	v_mov_b32_e32 v38, v35
	v_pk_add_f32 v[18:19], v[18:19], v[38:39]
	s_nop 0
	v_pk_add_f32 v[18:19], v[18:19], v[20:21]
	v_mov_b32_e32 v20, v42
	v_mov_b32_e32 v21, v46
	v_mov_b32_e32 v46, v43
	v_pk_add_f32 v[20:21], v[20:21], v[46:47]
	v_lshlrev_b64 v[42:43], 5, v[90:91]
	v_pk_add_f32 v[20:21], v[20:21], v[22:23]
	v_mov_b32_e32 v23, v18
	v_mov_b32_e32 v22, v20
	v_mov_b32_e32 v18, v21
	v_pk_add_f32 v[18:19], v[22:23], v[18:19]
	v_lshl_add_u64 v[42:43], s[6:7], 0, v[42:43]
	v_pk_fma_f32 v[18:19], v[18:19], s[74:75], v[214:215] op_sel_hi:[1,0,0]
	s_nop 0
	v_mul_f32_e32 v20, 0x4b800000, v19
	v_cmp_gt_f32_e64 s[46:47], s1, v19
	v_cmp_gt_f32_e32 vcc, s1, v18
	s_nop 0
	v_cndmask_b32_e64 v19, v19, v20, s[46:47]
	v_rsq_f32_e32 v19, v19
	s_nop 0
	v_mul_f32_e32 v20, 0x45800000, v19
	v_cndmask_b32_e64 v208, v19, v20, s[46:47]
	v_mul_f32_e32 v19, 0x4b800000, v18
	v_cndmask_b32_e32 v18, v18, v19, vcc
	v_rsq_f32_e32 v18, v18
	s_nop 0
	v_mul_f32_e32 v19, 0x45800000, v18
	v_cndmask_b32_e32 v206, v18, v19, vcc
	v_lshlrev_b64 v[18:19], 5, v[178:179]
	v_lshl_add_u64 v[18:19], s[6:7], 0, v[18:19]
	global_load_dwordx4 v[30:33], v[18:19], off
	global_load_dwordx4 v[26:29], v[18:19], off offset:16
	v_lshlrev_b64 v[18:19], 5, v[132:133]
	v_lshl_add_u64 v[18:19], s[6:7], 0, v[18:19]
	global_load_dwordx4 v[38:41], v[18:19], off
	global_load_dwordx4 v[34:37], v[18:19], off offset:16
	v_lshlrev_b64 v[18:19], 5, v[130:131]
	v_lshl_add_u64 v[18:19], s[6:7], 0, v[18:19]
	global_load_dwordx4 v[22:25], v[18:19], off
	s_nop 0
	global_load_dwordx4 v[18:21], v[18:19], off offset:16
	s_nop 0
	global_load_dwordx4 v[46:49], v[42:43], off
	s_nop 0
	global_load_dwordx4 v[42:45], v[42:43], off offset:16
	s_waitcnt vmcnt(7)
	v_mov_b32_e32 v230, v30
	s_waitcnt vmcnt(6)
	v_mov_b32_e32 v231, v26
	v_mov_b32_e32 v26, v31
	v_mov_b32_e32 v30, v32
	v_mov_b32_e32 v31, v28
	v_mov_b32_e32 v28, v33
	v_pk_add_f32 v[26:27], v[230:231], v[26:27]
	v_pk_add_f32 v[28:29], v[30:31], v[28:29]
	s_waitcnt vmcnt(5)
	v_mov_b32_e32 v30, v40
	v_pk_add_f32 v[26:27], v[26:27], v[28:29]
	v_mov_b32_e32 v28, v38
	s_waitcnt vmcnt(4)
	v_mov_b32_e32 v29, v34
	v_mov_b32_e32 v34, v39
	v_mov_b32_e32 v31, v36
	v_mov_b32_e32 v36, v41
	v_pk_add_f32 v[28:29], v[28:29], v[34:35]
	v_pk_add_f32 v[30:31], v[30:31], v[36:37]
	s_nop 0
	v_pk_add_f32 v[28:29], v[28:29], v[30:31]
	v_mov_b32_e32 v31, v26
	v_mov_b32_e32 v30, v28
	v_mov_b32_e32 v26, v29
	v_pk_add_f32 v[26:27], v[30:31], v[26:27]
	s_waitcnt vmcnt(3)
	v_mov_b32_e32 v30, v22
	s_waitcnt vmcnt(2)
	v_mov_b32_e32 v31, v18
	v_mov_b32_e32 v18, v23
	v_mov_b32_e32 v22, v24
	v_mov_b32_e32 v23, v20
	v_mov_b32_e32 v20, v25
	v_pk_add_f32 v[18:19], v[30:31], v[18:19]
	v_pk_add_f32 v[20:21], v[22:23], v[20:21]
	s_waitcnt vmcnt(1)
	v_mov_b32_e32 v22, v48
	v_pk_add_f32 v[18:19], v[18:19], v[20:21]
	v_mov_b32_e32 v20, v46
	s_waitcnt vmcnt(0)
; __device__ __forceinline__ void rstd8(float (&r)[8], const float* ssp, int row0) {
;     ...
;         for (int q = 0; q < 4; ++q) r[h * 4 + q] = rsqrtf((((a[q].x + a[q].y) + (a[q].z + a[q].w)) + ((b[q].x + b[q].y) + (b[q].z + b[q].w))) * (1.f / D) + EPS);
;     __device__ __forceinline__ void operator()(AccT& acc, const Unit& u, int wr, int wc, int fr, int fq) const {
;     ...
;         for (int ai = 0; ai < 2; ++ai)
; #pragma unroll
;             for (int m = 0; m < 4; ++m) { const int row = row0 + ai * 128 + m * 16; const float rstd = rs[ai * 4 + m];
; #pragma unroll
;                 for (int bj = 0; bj < 2; ++bj) { float* op = out + (size_t)row * D + col0 + bj * 128;
;                     *(f32x4*)op = acc[ai][bj][m][0] * rstd * gv[bj][0]; *(f32x4*)(op + 4) = acc[ai][bj][m][1] * rstd * gv[bj][1]; } }
	v_mov_b32_e32 v21, v42
	v_mov_b32_e32 v42, v47
	v_mov_b32_e32 v23, v44
	v_mov_b32_e32 v44, v49
	v_pk_add_f32 v[20:21], v[20:21], v[42:43]
	v_pk_add_f32 v[22:23], v[22:23], v[44:45]
	v_pk_mul_f32 v[24:25], v[128:129], v[212:213] op_sel_hi:[1,0]
	v_pk_add_f32 v[20:21], v[20:21], v[22:23]
	v_mov_b32_e32 v23, v18
	v_mov_b32_e32 v22, v20
	v_mov_b32_e32 v18, v21
	v_pk_add_f32 v[18:19], v[22:23], v[18:19]
	v_lshlrev_b64 v[22:23], 13, v[172:173]
	v_lshl_add_u64 v[22:23], s[50:51], 0, v[22:23]
	v_lshl_add_u64 v[30:31], v[22:23], 0, v[196:197]
	v_pk_mul_f32 v[22:23], v[126:127], v[212:213] op_sel_hi:[1,0]
	v_pk_mul_f32 v[24:25], v[16:17], v[24:25]
	v_pk_mul_f32 v[22:23], v[14:15], v[22:23]
	v_mbcnt_lo_u32_b32 v248, -1, 0
	v_mbcnt_hi_u32_b32 v248, -1, v248
	v_and_b32_e32 v248, 8, v248
	v_cmp_ne_u32_e64 s[100:101], 0, v248
	v_mov_b32_e32 v250, 0xffff0010
	v_mov_b32_e32 v251, -1
	v_mov_b32_e32 v240, 0
	s_nop 1
	v_cndmask_b32_e64 v248, 0, v250, s[100:101]
	v_cndmask_b32_e64 v249, 0, v251, s[100:101]
	v_mov_b32_e32 v251, 0x10010
	v_cndmask_b32_e64 v250, v251, v240, s[100:101]
	v_mov_b32_e32 v251, 0
	v_pk_fma_f32 v[26:27], v[26:27], s[74:75], v[214:215] op_sel_hi:[1,0,0]
	v_pk_fma_f32 v[18:19], v[18:19], s[74:75], v[214:215] op_sel_hi:[1,0,0]
	v_pk_mul_f32 v[236:237], v[122:123], v[212:213] op_sel_hi:[1,0]
	v_pk_mul_f32 v[238:239], v[124:125], v[212:213] op_sel_hi:[1,0]
	v_pk_mul_f32 v[236:237], v[10:11], v[236:237]
	v_pk_mul_f32 v[238:239], v[12:13], v[238:239]
	s_nop 1
	v_mov_b32_dpp v240, v236 row_ror:8 row_mask:0xf bank_mask:0xf
	v_mov_b32_dpp v241, v237 row_ror:8 row_mask:0xf bank_mask:0xf
	v_mov_b32_dpp v242, v238 row_ror:8 row_mask:0xf bank_mask:0xf
	v_mov_b32_dpp v243, v239 row_ror:8 row_mask:0xf bank_mask:0xf
	v_cndmask_b32_e64 v244, v22, v240, s[100:101]
	v_cndmask_b32_e64 v245, v23, v241, s[100:101]
	v_cndmask_b32_e64 v246, v24, v242, s[100:101]
	v_cndmask_b32_e64 v247, v25, v243, s[100:101]
	v_cndmask_b32_e64 v22, v240, v22, s[100:101]
	v_cndmask_b32_e64 v23, v241, v23, s[100:101]
	v_cndmask_b32_e64 v24, v242, v24, s[100:101]
	v_cndmask_b32_e64 v25, v243, v25, s[100:101]
	v_lshl_add_u64 v[240:241], v[30:31], 0, v[248:249]
	v_lshl_add_u64 v[242:243], v[30:31], 0, v[250:251]
	global_store_dwordx4 v[240:241], v[244:247], off
	global_store_dwordx4 v[242:243], v[22:25], off
	s_nop 1
	v_mul_f32_e32 v28, 0x4b800000, v27
	v_cmp_gt_f32_e64 s[46:47], s1, v27
	v_pk_mul_f32 v[22:23], v[118:119], v[212:213] op_sel_hi:[1,0]
	v_pk_mul_f32 v[24:25], v[120:121], v[212:213] op_sel_hi:[1,0]
	v_pk_mul_f32 v[22:23], v[6:7], v[22:23]
	v_pk_mul_f32 v[24:25], v[8:9], v[24:25]
	v_cndmask_b32_e64 v27, v27, v28, s[46:47]
	v_rsq_f32_e32 v27, v27
	v_pk_mul_f32 v[236:237], v[114:115], v[212:213] op_sel_hi:[1,0]
	v_pk_mul_f32 v[238:239], v[116:117], v[212:213] op_sel_hi:[1,0]
	v_pk_mul_f32 v[236:237], v[2:3], v[236:237]
	v_pk_mul_f32 v[238:239], v[4:5], v[238:239]
	s_nop 1
	v_mov_b32_dpp v240, v236 row_ror:8 row_mask:0xf bank_mask:0xf
	v_mov_b32_dpp v241, v237 row_ror:8 row_mask:0xf bank_mask:0xf
	v_mov_b32_dpp v242, v238 row_ror:8 row_mask:0xf bank_mask:0xf
	v_mov_b32_dpp v243, v239 row_ror:8 row_mask:0xf bank_mask:0xf
	v_cndmask_b32_e64 v244, v22, v240, s[100:101]
	v_cndmask_b32_e64 v245, v23, v241, s[100:101]
	v_cndmask_b32_e64 v246, v24, v242, s[100:101]
	v_cndmask_b32_e64 v247, v25, v243, s[100:101]
	v_cndmask_b32_e64 v22, v240, v22, s[100:101]
	v_cndmask_b32_e64 v23, v241, v23, s[100:101]
	v_cndmask_b32_e64 v24, v242, v24, s[100:101]
	v_cndmask_b32_e64 v25, v243, v25, s[100:101]
	v_lshl_add_u64 v[240:241], v[30:31], 0, v[248:249]
	v_lshl_add_u64 v[242:243], v[30:31], 0, v[250:251]
	global_store_dwordx4 v[240:241], v[244:247], off offset:512
	global_store_dwordx4 v[242:243], v[22:25], off offset:512
	s_nop 1
	v_mul_f32_e32 v28, 0x45800000, v27
	v_cndmask_b32_e64 v28, v27, v28, s[46:47]
	v_lshlrev_b64 v[22:23], 13, v[174:175]
	v_lshl_add_u64 v[22:23], s[50:51], 0, v[22:23]
	v_lshl_add_u64 v[30:31], v[22:23], 0, v[196:197]
	v_pk_mul_f32 v[22:23], v[110:111], v[210:211] op_sel_hi:[1,0]
	v_pk_mul_f32 v[24:25], v[112:113], v[210:211] op_sel_hi:[1,0]
	v_pk_mul_f32 v[22:23], v[14:15], v[22:23]
	v_pk_mul_f32 v[24:25], v[16:17], v[24:25]
	v_cmp_gt_f32_e32 vcc, s1, v26
	v_mul_f32_e32 v27, 0x4b800000, v26
	v_pk_mul_f32 v[236:237], v[106:107], v[210:211] op_sel_hi:[1,0]
	v_pk_mul_f32 v[238:239], v[108:109], v[210:211] op_sel_hi:[1,0]
	v_pk_mul_f32 v[236:237], v[10:11], v[236:237]
	v_pk_mul_f32 v[238:239], v[12:13], v[238:239]
	s_nop 1
	v_mov_b32_dpp v240, v236 row_ror:8 row_mask:0xf bank_mask:0xf
	v_mov_b32_dpp v241, v237 row_ror:8 row_mask:0xf bank_mask:0xf
	v_mov_b32_dpp v242, v238 row_ror:8 row_mask:0xf bank_mask:0xf
	v_mov_b32_dpp v243, v239 row_ror:8 row_mask:0xf bank_mask:0xf
	v_cndmask_b32_e64 v244, v22, v240, s[100:101]
	v_cndmask_b32_e64 v245, v23, v241, s[100:101]
	v_cndmask_b32_e64 v246, v24, v242, s[100:101]
	v_cndmask_b32_e64 v247, v25, v243, s[100:101]
	v_cndmask_b32_e64 v22, v240, v22, s[100:101]
	v_cndmask_b32_e64 v23, v241, v23, s[100:101]
	v_cndmask_b32_e64 v24, v242, v24, s[100:101]
	v_cndmask_b32_e64 v25, v243, v25, s[100:101]
	v_lshl_add_u64 v[240:241], v[30:31], 0, v[248:249]
	v_lshl_add_u64 v[242:243], v[30:31], 0, v[250:251]
	global_store_dwordx4 v[240:241], v[244:247], off
	global_store_dwordx4 v[242:243], v[22:25], off
	s_nop 1
	v_cndmask_b32_e32 v26, v26, v27, vcc
	v_rsq_f32_e32 v26, v26
	v_pk_mul_f32 v[22:23], v[102:103], v[210:211] op_sel_hi:[1,0]
	v_pk_mul_f32 v[24:25], v[104:105], v[210:211] op_sel_hi:[1,0]
	v_pk_mul_f32 v[22:23], v[6:7], v[22:23]
	v_pk_mul_f32 v[24:25], v[8:9], v[24:25]
	v_mul_f32_e32 v27, 0x45800000, v26
	v_cndmask_b32_e32 v26, v26, v27, vcc
;     __device__ __forceinline__ void operator()(AccT& acc, const Unit& u, int wr, int wc, int fr, int fq) const {
;     ...
;         for (int ai = 0; ai < 2; ++ai)
; #pragma unroll
;             for (int m = 0; m < 4; ++m) { const int row = row0 + ai * 128 + m * 16; const float rstd = rs[ai * 4 + m];
; #pragma unroll
;                 for (int bj = 0; bj < 2; ++bj) { float* op = out + (size_t)row * D + col0 + bj * 128;
;                     *(f32x4*)op = acc[ai][bj][m][0] * rstd * gv[bj][0]; *(f32x4*)(op + 4) = acc[ai][bj][m][1] * rstd * gv[bj][1]; } }
	v_pk_mul_f32 v[236:237], v[98:99], v[210:211] op_sel_hi:[1,0]
	v_pk_mul_f32 v[238:239], v[100:101], v[210:211] op_sel_hi:[1,0]
	v_pk_mul_f32 v[236:237], v[2:3], v[236:237]
	v_pk_mul_f32 v[238:239], v[4:5], v[238:239]
	s_nop 1
	v_mov_b32_dpp v240, v236 row_ror:8 row_mask:0xf bank_mask:0xf
	v_mov_b32_dpp v241, v237 row_ror:8 row_mask:0xf bank_mask:0xf
	v_mov_b32_dpp v242, v238 row_ror:8 row_mask:0xf bank_mask:0xf
	v_mov_b32_dpp v243, v239 row_ror:8 row_mask:0xf bank_mask:0xf
	v_cndmask_b32_e64 v244, v22, v240, s[100:101]
	v_cndmask_b32_e64 v245, v23, v241, s[100:101]
	v_cndmask_b32_e64 v246, v24, v242, s[100:101]
	v_cndmask_b32_e64 v247, v25, v243, s[100:101]
	v_cndmask_b32_e64 v22, v240, v22, s[100:101]
	v_cndmask_b32_e64 v23, v241, v23, s[100:101]
	v_cndmask_b32_e64 v24, v242, v24, s[100:101]
	v_cndmask_b32_e64 v25, v243, v25, s[100:101]
	v_lshl_add_u64 v[240:241], v[30:31], 0, v[248:249]
	v_lshl_add_u64 v[242:243], v[30:31], 0, v[250:251]
	global_store_dwordx4 v[240:241], v[244:247], off offset:512
	global_store_dwordx4 v[242:243], v[22:25], off offset:512
	s_nop 1
	v_mul_f32_e32 v20, 0x4b800000, v19
	v_cmp_gt_f32_e64 s[46:47], s1, v19
	v_lshlrev_b64 v[22:23], 13, v[170:171]
	v_lshl_add_u64 v[22:23], s[50:51], 0, v[22:23]
	v_lshl_add_u64 v[30:31], v[22:23], 0, v[196:197]
	v_pk_mul_f32 v[22:23], v[94:95], v[208:209] op_sel_hi:[1,0]
	v_pk_mul_f32 v[24:25], v[96:97], v[208:209] op_sel_hi:[1,0]
	v_pk_mul_f32 v[22:23], v[14:15], v[22:23]
	v_pk_mul_f32 v[24:25], v[16:17], v[24:25]
	v_cndmask_b32_e64 v19, v19, v20, s[46:47]
	v_rsq_f32_e32 v19, v19
	v_pk_mul_f32 v[236:237], v[142:143], v[208:209] op_sel_hi:[1,0]
	v_pk_mul_f32 v[238:239], v[92:93], v[208:209] op_sel_hi:[1,0]
	v_pk_mul_f32 v[236:237], v[10:11], v[236:237]
	v_pk_mul_f32 v[238:239], v[12:13], v[238:239]
	s_nop 1
	v_mov_b32_dpp v240, v236 row_ror:8 row_mask:0xf bank_mask:0xf
	v_mov_b32_dpp v241, v237 row_ror:8 row_mask:0xf bank_mask:0xf
	v_mov_b32_dpp v242, v238 row_ror:8 row_mask:0xf bank_mask:0xf
	v_mov_b32_dpp v243, v239 row_ror:8 row_mask:0xf bank_mask:0xf
	v_cndmask_b32_e64 v244, v22, v240, s[100:101]
	v_cndmask_b32_e64 v245, v23, v241, s[100:101]
	v_cndmask_b32_e64 v246, v24, v242, s[100:101]
	v_cndmask_b32_e64 v247, v25, v243, s[100:101]
	v_cndmask_b32_e64 v22, v240, v22, s[100:101]
	v_cndmask_b32_e64 v23, v241, v23, s[100:101]
	v_cndmask_b32_e64 v24, v242, v24, s[100:101]
	v_cndmask_b32_e64 v25, v243, v25, s[100:101]
	v_lshl_add_u64 v[240:241], v[30:31], 0, v[248:249]
	v_lshl_add_u64 v[242:243], v[30:31], 0, v[250:251]
	global_store_dwordx4 v[240:241], v[244:247], off
	global_store_dwordx4 v[242:243], v[22:25], off
	s_nop 1
	v_mul_f32_e32 v20, 0x45800000, v19
	v_cndmask_b32_e64 v20, v19, v20, s[46:47]
	v_pk_mul_f32 v[22:23], v[144:145], v[208:209] op_sel_hi:[1,0]
	v_pk_mul_f32 v[24:25], v[134:135], v[208:209] op_sel_hi:[1,0]
	v_pk_mul_f32 v[22:23], v[6:7], v[22:23]
	v_pk_mul_f32 v[24:25], v[8:9], v[24:25]
	v_cmp_gt_f32_e32 vcc, s1, v18
	v_mul_f32_e32 v19, 0x4b800000, v18
	v_pk_mul_f32 v[236:237], v[146:147], v[208:209] op_sel_hi:[1,0]
	v_pk_mul_f32 v[238:239], v[136:137], v[208:209] op_sel_hi:[1,0]
	v_pk_mul_f32 v[236:237], v[2:3], v[236:237]
	v_pk_mul_f32 v[238:239], v[4:5], v[238:239]
	s_nop 1
	v_mov_b32_dpp v240, v236 row_ror:8 row_mask:0xf bank_mask:0xf
	v_mov_b32_dpp v241, v237 row_ror:8 row_mask:0xf bank_mask:0xf
	v_mov_b32_dpp v242, v238 row_ror:8 row_mask:0xf bank_mask:0xf
	v_mov_b32_dpp v243, v239 row_ror:8 row_mask:0xf bank_mask:0xf
	v_cndmask_b32_e64 v244, v22, v240, s[100:101]
	v_cndmask_b32_e64 v245, v23, v241, s[100:101]
	v_cndmask_b32_e64 v246, v24, v242, s[100:101]
	v_cndmask_b32_e64 v247, v25, v243, s[100:101]
	v_cndmask_b32_e64 v22, v240, v22, s[100:101]
	v_cndmask_b32_e64 v23, v241, v23, s[100:101]
	v_cndmask_b32_e64 v24, v242, v24, s[100:101]
	v_cndmask_b32_e64 v25, v243, v25, s[100:101]
	v_lshl_add_u64 v[240:241], v[30:31], 0, v[248:249]
	v_lshl_add_u64 v[242:243], v[30:31], 0, v[250:251]
	global_store_dwordx4 v[240:241], v[244:247], off offset:512
	global_store_dwordx4 v[242:243], v[22:25], off offset:512
	s_nop 1
	v_cndmask_b32_e32 v18, v18, v19, vcc
	v_rsq_f32_e32 v18, v18
	v_lshlrev_b64 v[22:23], 13, v[168:169]
	v_lshl_add_u64 v[22:23], s[50:51], 0, v[22:23]
	v_lshl_add_u64 v[30:31], v[22:23], 0, v[196:197]
	v_pk_mul_f32 v[22:23], v[148:149], v[206:207] op_sel_hi:[1,0]
	v_pk_mul_f32 v[24:25], v[138:139], v[206:207] op_sel_hi:[1,0]
	v_pk_mul_f32 v[22:23], v[14:15], v[22:23]
	v_pk_mul_f32 v[24:25], v[16:17], v[24:25]
	v_mul_f32_e32 v19, 0x45800000, v18
	v_cndmask_b32_e32 v18, v18, v19, vcc
	v_pk_mul_f32 v[236:237], v[150:151], v[206:207] op_sel_hi:[1,0]
	v_pk_mul_f32 v[238:239], v[140:141], v[206:207] op_sel_hi:[1,0]
	v_pk_mul_f32 v[236:237], v[10:11], v[236:237]
	v_pk_mul_f32 v[238:239], v[12:13], v[238:239]
	s_nop 1
	v_mov_b32_dpp v240, v236 row_ror:8 row_mask:0xf bank_mask:0xf
	v_mov_b32_dpp v241, v237 row_ror:8 row_mask:0xf bank_mask:0xf
	v_mov_b32_dpp v242, v238 row_ror:8 row_mask:0xf bank_mask:0xf
	v_mov_b32_dpp v243, v239 row_ror:8 row_mask:0xf bank_mask:0xf
	v_cndmask_b32_e64 v244, v22, v240, s[100:101]
	v_cndmask_b32_e64 v245, v23, v241, s[100:101]
	v_cndmask_b32_e64 v246, v24, v242, s[100:101]
	v_cndmask_b32_e64 v247, v25, v243, s[100:101]
	v_cndmask_b32_e64 v22, v240, v22, s[100:101]
	v_cndmask_b32_e64 v23, v241, v23, s[100:101]
	v_cndmask_b32_e64 v24, v242, v24, s[100:101]
	v_cndmask_b32_e64 v25, v243, v25, s[100:101]
	v_lshl_add_u64 v[240:241], v[30:31], 0, v[248:249]
	v_lshl_add_u64 v[242:243], v[30:31], 0, v[250:251]
	global_store_dwordx4 v[240:241], v[244:247], off
	global_store_dwordx4 v[242:243], v[22:25], off
	s_nop 1
;     __device__ __forceinline__ void operator()(AccT& acc, const Unit& u, int wr, int wc, int fr, int fq) const {
;     ...
;         for (int ai = 0; ai < 2; ++ai)
; #pragma unroll
;             for (int m = 0; m < 4; ++m) { const int row = row0 + ai * 128 + m * 16; const float rstd = rs[ai * 4 + m];
; #pragma unroll
;                 for (int bj = 0; bj < 2; ++bj) { float* op = out + (size_t)row * D + col0 + bj * 128;
;                     *(f32x4*)op = acc[ai][bj][m][0] * rstd * gv[bj][0]; *(f32x4*)(op + 4) = acc[ai][bj][m][1] * rstd * gv[bj][1]; } }
	s_andn2_b64 vcc, exec, s[44:45]
	s_nop 0
	v_pk_mul_f32 v[22:23], v[156:157], v[206:207] op_sel_hi:[1,0]
	v_pk_mul_f32 v[24:25], v[152:153], v[206:207] op_sel_hi:[1,0]
	v_pk_mul_f32 v[22:23], v[6:7], v[22:23]
	v_pk_mul_f32 v[24:25], v[8:9], v[24:25]
	s_nop 1
	v_pk_mul_f32 v[236:237], v[176:177], v[206:207] op_sel_hi:[1,0]
	v_pk_mul_f32 v[238:239], v[154:155], v[206:207] op_sel_hi:[1,0]
	v_pk_mul_f32 v[236:237], v[2:3], v[236:237]
	v_pk_mul_f32 v[238:239], v[4:5], v[238:239]
	s_nop 1
	v_mov_b32_dpp v240, v236 row_ror:8 row_mask:0xf bank_mask:0xf
	v_mov_b32_dpp v241, v237 row_ror:8 row_mask:0xf bank_mask:0xf
	v_mov_b32_dpp v242, v238 row_ror:8 row_mask:0xf bank_mask:0xf
	v_mov_b32_dpp v243, v239 row_ror:8 row_mask:0xf bank_mask:0xf
	v_cndmask_b32_e64 v244, v22, v240, s[100:101]
	v_cndmask_b32_e64 v245, v23, v241, s[100:101]
	v_cndmask_b32_e64 v246, v24, v242, s[100:101]
	v_cndmask_b32_e64 v247, v25, v243, s[100:101]
	v_cndmask_b32_e64 v22, v240, v22, s[100:101]
	v_cndmask_b32_e64 v23, v241, v23, s[100:101]
	v_cndmask_b32_e64 v24, v242, v24, s[100:101]
	v_cndmask_b32_e64 v25, v243, v25, s[100:101]
	v_lshl_add_u64 v[240:241], v[30:31], 0, v[248:249]
	v_lshl_add_u64 v[242:243], v[30:31], 0, v[250:251]
	global_store_dwordx4 v[240:241], v[244:247], off offset:512
	global_store_dwordx4 v[242:243], v[22:25], off offset:512
	s_nop 1
	s_nop 1
	v_lshlrev_b64 v[22:23], 13, v[178:179]
	v_lshl_add_u64 v[22:23], s[50:51], 0, v[22:23]
	v_lshl_add_u64 v[30:31], v[22:23], 0, v[196:197]
	v_pk_mul_f32 v[22:23], v[62:63], v[28:29] op_sel_hi:[1,0]
	v_pk_mul_f32 v[24:25], v[64:65], v[28:29] op_sel_hi:[1,0]
	v_pk_mul_f32 v[22:23], v[14:15], v[22:23]
	v_pk_mul_f32 v[24:25], v[16:17], v[24:25]
	s_nop 1
	v_pk_mul_f32 v[236:237], v[58:59], v[28:29] op_sel_hi:[1,0]
	v_pk_mul_f32 v[238:239], v[60:61], v[28:29] op_sel_hi:[1,0]
	v_pk_mul_f32 v[236:237], v[10:11], v[236:237]
	v_pk_mul_f32 v[238:239], v[12:13], v[238:239]
	s_nop 1
	v_mov_b32_dpp v240, v236 row_ror:8 row_mask:0xf bank_mask:0xf
	v_mov_b32_dpp v241, v237 row_ror:8 row_mask:0xf bank_mask:0xf
	v_mov_b32_dpp v242, v238 row_ror:8 row_mask:0xf bank_mask:0xf
	v_mov_b32_dpp v243, v239 row_ror:8 row_mask:0xf bank_mask:0xf
	v_cndmask_b32_e64 v244, v22, v240, s[100:101]
	v_cndmask_b32_e64 v245, v23, v241, s[100:101]
	v_cndmask_b32_e64 v246, v24, v242, s[100:101]
	v_cndmask_b32_e64 v247, v25, v243, s[100:101]
	v_cndmask_b32_e64 v22, v240, v22, s[100:101]
	v_cndmask_b32_e64 v23, v241, v23, s[100:101]
	v_cndmask_b32_e64 v24, v242, v24, s[100:101]
	v_cndmask_b32_e64 v25, v243, v25, s[100:101]
	v_lshl_add_u64 v[240:241], v[30:31], 0, v[248:249]
	v_lshl_add_u64 v[242:243], v[30:31], 0, v[250:251]
	global_store_dwordx4 v[240:241], v[244:247], off
	global_store_dwordx4 v[242:243], v[22:25], off
	s_nop 1
	s_nop 1
	v_pk_mul_f32 v[22:23], v[54:55], v[28:29] op_sel_hi:[1,0]
	v_pk_mul_f32 v[24:25], v[56:57], v[28:29] op_sel_hi:[1,0]
	v_pk_mul_f32 v[22:23], v[6:7], v[22:23]
	v_pk_mul_f32 v[24:25], v[8:9], v[24:25]
	s_nop 1
	v_pk_mul_f32 v[236:237], v[50:51], v[28:29] op_sel_hi:[1,0]
	v_pk_mul_f32 v[238:239], v[52:53], v[28:29] op_sel_hi:[1,0]
	v_pk_mul_f32 v[236:237], v[2:3], v[236:237]
	v_pk_mul_f32 v[238:239], v[4:5], v[238:239]
	s_nop 1
	v_mov_b32_dpp v240, v236 row_ror:8 row_mask:0xf bank_mask:0xf
	v_mov_b32_dpp v241, v237 row_ror:8 row_mask:0xf bank_mask:0xf
	v_mov_b32_dpp v242, v238 row_ror:8 row_mask:0xf bank_mask:0xf
	v_mov_b32_dpp v243, v239 row_ror:8 row_mask:0xf bank_mask:0xf
	v_cndmask_b32_e64 v244, v22, v240, s[100:101]
	v_cndmask_b32_e64 v245, v23, v241, s[100:101]
	v_cndmask_b32_e64 v246, v24, v242, s[100:101]
	v_cndmask_b32_e64 v247, v25, v243, s[100:101]
	v_cndmask_b32_e64 v22, v240, v22, s[100:101]
	v_cndmask_b32_e64 v23, v241, v23, s[100:101]
	v_cndmask_b32_e64 v24, v242, v24, s[100:101]
	v_cndmask_b32_e64 v25, v243, v25, s[100:101]
	v_lshl_add_u64 v[240:241], v[30:31], 0, v[248:249]
	v_lshl_add_u64 v[242:243], v[30:31], 0, v[250:251]
	global_store_dwordx4 v[240:241], v[244:247], off offset:512
	global_store_dwordx4 v[242:243], v[22:25], off offset:512
	s_nop 1
	s_nop 1
	v_lshlrev_b64 v[22:23], 13, v[132:133]
	v_lshl_add_u64 v[22:23], s[50:51], 0, v[22:23]
	v_lshl_add_u64 v[28:29], v[22:23], 0, v[196:197]
	v_pk_mul_f32 v[22:23], v[180:181], v[26:27] op_sel_hi:[1,0]
	v_pk_mul_f32 v[24:25], v[86:87], v[26:27] op_sel_hi:[1,0]
	v_pk_mul_f32 v[22:23], v[14:15], v[22:23]
	v_pk_mul_f32 v[24:25], v[16:17], v[24:25]
	s_nop 1
	v_pk_mul_f32 v[236:237], v[182:183], v[26:27] op_sel_hi:[1,0]
	v_pk_mul_f32 v[238:239], v[88:89], v[26:27] op_sel_hi:[1,0]
	v_pk_mul_f32 v[236:237], v[10:11], v[236:237]
	v_pk_mul_f32 v[238:239], v[12:13], v[238:239]
	s_nop 1
	v_mov_b32_dpp v240, v236 row_ror:8 row_mask:0xf bank_mask:0xf
	v_mov_b32_dpp v241, v237 row_ror:8 row_mask:0xf bank_mask:0xf
	v_mov_b32_dpp v242, v238 row_ror:8 row_mask:0xf bank_mask:0xf
	v_mov_b32_dpp v243, v239 row_ror:8 row_mask:0xf bank_mask:0xf
	v_cndmask_b32_e64 v244, v22, v240, s[100:101]
	v_cndmask_b32_e64 v245, v23, v241, s[100:101]
	v_cndmask_b32_e64 v246, v24, v242, s[100:101]
;     __device__ __forceinline__ void operator()(AccT& acc, const Unit& u, int wr, int wc, int fr, int fq) const {
;     ...
;         for (int ai = 0; ai < 2; ++ai)
; #pragma unroll
;             for (int m = 0; m < 4; ++m) { const int row = row0 + ai * 128 + m * 16; const float rstd = rs[ai * 4 + m];
; #pragma unroll
;                 for (int bj = 0; bj < 2; ++bj) { float* op = out + (size_t)row * D + col0 + bj * 128;
;                     *(f32x4*)op = acc[ai][bj][m][0] * rstd * gv[bj][0]; *(f32x4*)(op + 4) = acc[ai][bj][m][1] * rstd * gv[bj][1]; } }
	v_cndmask_b32_e64 v247, v25, v243, s[100:101]
	v_cndmask_b32_e64 v22, v240, v22, s[100:101]
	v_cndmask_b32_e64 v23, v241, v23, s[100:101]
	v_cndmask_b32_e64 v24, v242, v24, s[100:101]
	v_cndmask_b32_e64 v25, v243, v25, s[100:101]
	v_lshl_add_u64 v[240:241], v[28:29], 0, v[248:249]
	v_lshl_add_u64 v[242:243], v[28:29], 0, v[250:251]
	global_store_dwordx4 v[240:241], v[244:247], off
	global_store_dwordx4 v[242:243], v[22:25], off
	s_nop 1
	s_nop 1
	v_pk_mul_f32 v[22:23], v[184:185], v[26:27] op_sel_hi:[1,0]
	v_pk_mul_f32 v[24:25], v[82:83], v[26:27] op_sel_hi:[1,0]
	v_pk_mul_f32 v[22:23], v[6:7], v[22:23]
	v_pk_mul_f32 v[24:25], v[8:9], v[24:25]
	s_nop 1
	v_pk_mul_f32 v[236:237], v[186:187], v[26:27] op_sel_hi:[1,0]
	v_pk_mul_f32 v[238:239], v[84:85], v[26:27] op_sel_hi:[1,0]
	v_pk_mul_f32 v[236:237], v[2:3], v[236:237]
	v_pk_mul_f32 v[238:239], v[4:5], v[238:239]
	s_nop 1
	v_mov_b32_dpp v240, v236 row_ror:8 row_mask:0xf bank_mask:0xf
	v_mov_b32_dpp v241, v237 row_ror:8 row_mask:0xf bank_mask:0xf
	v_mov_b32_dpp v242, v238 row_ror:8 row_mask:0xf bank_mask:0xf
	v_mov_b32_dpp v243, v239 row_ror:8 row_mask:0xf bank_mask:0xf
	v_cndmask_b32_e64 v244, v22, v240, s[100:101]
	v_cndmask_b32_e64 v245, v23, v241, s[100:101]
	v_cndmask_b32_e64 v246, v24, v242, s[100:101]
	v_cndmask_b32_e64 v247, v25, v243, s[100:101]
	v_cndmask_b32_e64 v22, v240, v22, s[100:101]
	v_cndmask_b32_e64 v23, v241, v23, s[100:101]
	v_cndmask_b32_e64 v24, v242, v24, s[100:101]
	v_cndmask_b32_e64 v25, v243, v25, s[100:101]
	v_lshl_add_u64 v[240:241], v[28:29], 0, v[248:249]
	v_lshl_add_u64 v[242:243], v[28:29], 0, v[250:251]
	global_store_dwordx4 v[240:241], v[244:247], off offset:512
	global_store_dwordx4 v[242:243], v[22:25], off offset:512
	s_nop 1
	s_nop 1
	v_lshlrev_b64 v[22:23], 13, v[130:131]
	v_lshl_add_u64 v[22:23], s[50:51], 0, v[22:23]
	v_lshl_add_u64 v[26:27], v[22:23], 0, v[196:197]
	v_pk_mul_f32 v[22:23], v[188:189], v[20:21] op_sel_hi:[1,0]
	v_pk_mul_f32 v[24:25], v[78:79], v[20:21] op_sel_hi:[1,0]
	v_pk_mul_f32 v[22:23], v[14:15], v[22:23]
	v_pk_mul_f32 v[24:25], v[16:17], v[24:25]
	s_nop 1
	v_pk_mul_f32 v[236:237], v[190:191], v[20:21] op_sel_hi:[1,0]
	v_pk_mul_f32 v[238:239], v[80:81], v[20:21] op_sel_hi:[1,0]
	v_pk_mul_f32 v[236:237], v[10:11], v[236:237]
	v_pk_mul_f32 v[238:239], v[12:13], v[238:239]
	s_nop 1
	v_mov_b32_dpp v240, v236 row_ror:8 row_mask:0xf bank_mask:0xf
	v_mov_b32_dpp v241, v237 row_ror:8 row_mask:0xf bank_mask:0xf
	v_mov_b32_dpp v242, v238 row_ror:8 row_mask:0xf bank_mask:0xf
	v_mov_b32_dpp v243, v239 row_ror:8 row_mask:0xf bank_mask:0xf
	v_cndmask_b32_e64 v244, v22, v240, s[100:101]
	v_cndmask_b32_e64 v245, v23, v241, s[100:101]
	v_cndmask_b32_e64 v246, v24, v242, s[100:101]
	v_cndmask_b32_e64 v247, v25, v243, s[100:101]
	v_cndmask_b32_e64 v22, v240, v22, s[100:101]
	v_cndmask_b32_e64 v23, v241, v23, s[100:101]
	v_cndmask_b32_e64 v24, v242, v24, s[100:101]
	v_cndmask_b32_e64 v25, v243, v25, s[100:101]
	v_lshl_add_u64 v[240:241], v[26:27], 0, v[248:249]
	v_lshl_add_u64 v[242:243], v[26:27], 0, v[250:251]
	global_store_dwordx4 v[240:241], v[244:247], off
	global_store_dwordx4 v[242:243], v[22:25], off
	s_nop 1
	s_nop 1
	v_pk_mul_f32 v[22:23], v[192:193], v[20:21] op_sel_hi:[1,0]
	v_pk_mul_f32 v[24:25], v[70:71], v[20:21] op_sel_hi:[1,0]
	v_pk_mul_f32 v[22:23], v[6:7], v[22:23]
	v_pk_mul_f32 v[24:25], v[8:9], v[24:25]
	global_store_dwordx4 v[26:27], v[22:25], off offset:512
	s_nop 1
	v_pk_mul_f32 v[24:25], v[194:195], v[20:21] op_sel_hi:[1,0]
	v_pk_mul_f32 v[20:21], v[72:73], v[20:21] op_sel_hi:[1,0]
	s_nop 0
	v_pk_mul_f32 v[22:23], v[4:5], v[20:21]
	v_pk_mul_f32 v[20:21], v[2:3], v[24:25]
	global_store_dwordx4 v[26:27], v[20:23], off offset:528
	v_pk_mul_f32 v[24:25], v[74:75], v[18:19] op_sel_hi:[1,0]
	s_nop 0
	v_lshlrev_b64 v[20:21], 13, v[90:91]
	v_lshl_add_u64 v[20:21], s[50:51], 0, v[20:21]
	v_pk_mul_f32 v[22:23], v[198:199], v[18:19] op_sel_hi:[1,0]
	v_lshl_add_u64 v[20:21], v[20:21], 0, v[196:197]
	v_pk_mul_f32 v[16:17], v[16:17], v[24:25]
	v_pk_mul_f32 v[14:15], v[14:15], v[22:23]
	global_store_dwordx4 v[20:21], v[14:17], off
	s_nop 1
	v_pk_mul_f32 v[14:15], v[200:201], v[18:19] op_sel_hi:[1,0]
	v_pk_mul_f32 v[16:17], v[76:77], v[18:19] op_sel_hi:[1,0]
	v_pk_mul_f32 v[10:11], v[10:11], v[14:15]
	v_pk_mul_f32 v[12:13], v[12:13], v[16:17]
	global_store_dwordx4 v[20:21], v[10:13], off offset:16
	s_nop 1
	v_pk_mul_f32 v[10:11], v[202:203], v[18:19] op_sel_hi:[1,0]
	v_pk_mul_f32 v[12:13], v[66:67], v[18:19] op_sel_hi:[1,0]
	v_pk_mul_f32 v[6:7], v[6:7], v[10:11]
	v_pk_mul_f32 v[8:9], v[8:9], v[12:13]
	global_store_dwordx4 v[20:21], v[6:9], off offset:512
	s_nop 1
	v_pk_mul_f32 v[6:7], v[204:205], v[18:19] op_sel_hi:[1,0]
	v_pk_mul_f32 v[8:9], v[68:69], v[18:19] op_sel_hi:[1,0]
	v_pk_mul_f32 v[2:3], v[2:3], v[6:7]
	v_pk_mul_f32 v[4:5], v[4:5], v[8:9]
	global_store_dwordx4 v[20:21], v[2:5], off offset:528
	s_mov_b64 s[100:101], 0x800
	s_cbranch_vccnz .LBB0_874
	s_andn2_b64 vcc, exec, s[2:3]
	s_cbranch_vccnz .LBB0_873
	s_barrier
	s_branch .LBB0_873
